# GEMM1: static s_setprio 1 for waves 4-7 before the tile loop, per-block setprio flips deleted (on top of cache hints)
# baseline (speedup 1.0000x reference)
.LBB0_153:
	s_cmp_lt_i32 s26, 2
	s_cselect_b64 s[4:5], -1, 0
	s_add_u32 s34, s76, 0x2000000
	s_addc_u32 s35, s77, 0
	s_add_u32 s28, s78, 0x3a00000
	s_addc_u32 s29, s79, 0
	s_and_b64 s[0:1], s[4:5], s[0:1]
	s_andn2_b64 vcc, exec, s[0:1]
	s_cbranch_vccnz .LBB0_186
	v_and_b32_e32 v10, 0x3ff, v0
	s_cmpk_gt_u32 s96, 0x6ff
	v_readfirstlane_b32 s0, v10
	s_cbranch_scc1 .LBB0_186
	s_lshr_b32 s98, s0, 8
	s_cmp_eq_u32 s98, 0
	s_cbranch_scc1 .Lprio_skip
	s_setprio 1
.Lprio_skip:
	v_lshrrev_b32_e32 v1, 5, v10
	v_lshrrev_b32_e32 v15, 1, v10
	v_and_b32_e32 v1, 4, v1
	v_bfe_u32 v2, v10, 2, 2
	v_and_b32_e32 v16, 24, v15
	v_or3_b32 v1, v1, v2, v16
	v_lshlrev_b32_e32 v2, 4, v10
	v_add_u32_e32 v11, 0x2000, v2
	v_lshrrev_b32_e32 v3, 7, v11
	s_movk_i32 s6, 0xe0
	v_and_b32_e32 v5, 32, v10
	v_and_or_b32 v4, v3, s6, v1
	v_bitop3_b32 v12, v2, v5, 48 bitop3:0x6c
	v_and_b32_e32 v13, 64, v10
	v_bfe_u32 v14, v10, 2, 4
	s_movk_i32 s6, 0xf0
	v_or_b32_e32 v2, v12, v13
	v_and_or_b32 v3, v3, s6, v14
	v_lshl_or_b32 v132, v3, 11, v2
	v_lshrrev_b32_e32 v3, 3, v10
	s_movk_i32 s6, 0x60
	s_add_u32 s2, s78, 0x800000
	v_and_or_b32 v1, v3, s6, v1
	s_movk_i32 s6, 0x70
	s_addc_u32 s24, s79, 0
	v_lshl_or_b32 v134, v1, 11, v2
	v_and_or_b32 v1, v3, s6, v14
	s_and_b32 s6, s96, 7
	s_lshr_b32 s7, s96, 3
	s_mulk_i32 s6, 0xe0
	s_add_i32 s6, s6, s7
	s_bfe_u32 s7, s6, 0x100005
	s_mulk_i32 s7, 0x2493
	s_lshr_b32 s7, s7, 16
	s_lshl_b32 s8, s7, 3
	s_mulk_i32 s7, 0xe0
	s_sub_i32 s6, s6, s7
	s_and_b32 s7, s6, 7
	s_lshr_b32 s1, s0, 6
	s_or_b32 s8, s7, s8
	s_bfe_u32 s9, s6, 0xd0003
	s_lshr_b32 s6, s6, 3
	s_lshr_b32 s12, s0, 8
	s_lshl_b32 s25, s1, 10
	s_lshl_b32 s10, s8, 19
	s_lshl_b32 s6, s6, 19
	s_add_u32 s54, s2, s6
	s_addc_u32 s55, s24, 0
	s_add_i32 s26, s25, 0
	s_add_i32 m0, s26, 0x10000
	v_lshl_or_b32 v130, v4, 11, v2
	global_load_lds_dwordx4 v134, s[54:55]
	s_add_i32 m0, s26, 0x12000
	s_add_u32 s6, s54, 0x40000
	global_load_lds_dwordx4 v130, s[54:55]
	s_addc_u32 s7, s55, 0
	s_add_i32 m0, s26, 0x14000
	v_lshl_or_b32 v136, v1, 11, v2
	global_load_lds_dwordx4 v134, s[6:7]
	s_add_i32 m0, s26, 0x16000
	s_add_u32 s52, s76, s10
	s_addc_u32 s53, s77, 0
	s_add_i32 s27, s26, 0x2000
	global_load_lds_dwordx4 v130, s[6:7]
	s_mov_b32 m0, s26
	s_add_u32 s6, s52, 0x40000
	global_load_lds_dwordx4 v136, s[52:53]
	s_mov_b32 m0, s27
	s_addc_u32 s7, s53, 0
	s_add_i32 s58, s26, 0x4000
	global_load_lds_dwordx4 v132, s[52:53]
	s_mov_b32 m0, s58
	s_add_i32 s59, s26, 0x6000
	global_load_lds_dwordx4 v136, s[6:7]
	s_mov_b32 m0, s59
	v_mov_b32_e32 v139, 0
	global_load_lds_dwordx4 v132, s[6:7]
	v_mov_b32_e32 v135, v139
	v_mov_b32_e32 v131, v139
	v_mov_b32_e32 v137, v139
	v_mov_b32_e32 v133, v139
	s_cmp_eq_u32 s12, 1
	s_mov_b32 s60, 0
	v_lshl_add_u64 v[8:9], s[54:55], 0, v[134:135]
	v_lshl_add_u64 v[4:5], s[54:55], 0, v[130:131]
	v_lshl_add_u64 v[2:3], s[52:53], 0, v[136:137]
	s_cselect_b64 s[6:7], -1, 0
	s_cmp_lg_u32 s12, 1
	v_lshl_add_u64 v[6:7], s[52:53], 0, v[132:133]
	s_cbranch_scc1 .LBB0_157
	s_barrier

.LBB0_163:
	ds_read_b128 v[152:155], v163
	ds_read_b128 v[166:169], v163 offset:1024
	ds_read_b128 v[170:173], v163 offset:2048
	ds_read_b128 v[174:177], v163 offset:3072
	ds_read_b128 v[178:181], v164
	ds_read_b128 v[182:185], v164 offset:1024
	ds_read_b128 v[186:189], v164 offset:2048
	ds_read_b128 v[190:193], v164 offset:3072
	s_add_u32 s33, s52, 0xfffc0080
	s_addc_u32 s54, s53, -1
	s_cmp_eq_u32 s92, 12
	s_cselect_b32 s57, s18, s54
	s_cselect_b32 s56, s19, s33
	s_cselect_b32 s55, s17, s91
	s_cselect_b32 s54, s21, s90
	v_lshl_add_u64 v[156:157], s[52:53], 0, v[142:143]
	s_add_i32 m0, s26, 0xc000
	ds_read_b128 v[194:197], v165
	ds_read_b128 v[198:201], v165 offset:1024
	ds_read_b128 v[202:205], v165 offset:2048
	ds_read_b128 v[206:209], v165 offset:3072
	ds_read_b128 v[210:213], v165 offset:4096
	ds_read_b128 v[214:217], v165 offset:5120
	ds_read_b128 v[218:221], v165 offset:6144
	ds_read_b128 v[222:225], v165 offset:7168
	global_load_lds_dwordx4 v[156:157], off
	v_lshl_add_u64 v[156:157], s[52:53], 0, v[144:145]
	s_add_i32 m0, s26, 0xe000
	s_nop 0
	global_load_lds_dwordx4 v[156:157], off
	s_waitcnt vmcnt(8)
	s_waitcnt lgkmcnt(0)
	s_barrier
	s_waitcnt lgkmcnt(0)
	v_mfma_f32_16x16x32_bf16 v[126:129], v[152:155], v[194:197], v[126:129]
	v_mfma_f32_16x16x32_bf16 v[122:125], v[170:173], v[194:197], v[122:125]
	v_mfma_f32_16x16x32_bf16 v[118:121], v[152:155], v[202:205], v[118:121]
	v_mfma_f32_16x16x32_bf16 v[114:117], v[170:173], v[202:205], v[114:117]
	v_mfma_f32_16x16x32_bf16 v[102:105], v[152:155], v[210:213], v[102:105]
	v_mfma_f32_16x16x32_bf16 v[98:101], v[170:173], v[210:213], v[98:101]
	v_mfma_f32_16x16x32_bf16 v[86:89], v[152:155], v[218:221], v[86:89]
	v_mfma_f32_16x16x32_bf16 v[82:85], v[170:173], v[218:221], v[82:85]
	v_mfma_f32_16x16x32_bf16 v[126:129], v[166:169], v[198:201], v[126:129]
	v_mfma_f32_16x16x32_bf16 v[122:125], v[174:177], v[198:201], v[122:125]
	v_mfma_f32_16x16x32_bf16 v[118:121], v[166:169], v[206:209], v[118:121]
	v_mfma_f32_16x16x32_bf16 v[114:117], v[174:177], v[206:209], v[114:117]
	v_mfma_f32_16x16x32_bf16 v[102:105], v[166:169], v[214:217], v[102:105]
	v_mfma_f32_16x16x32_bf16 v[98:101], v[174:177], v[214:217], v[98:101]
	v_mfma_f32_16x16x32_bf16 v[86:89], v[166:169], v[222:225], v[86:89]
	v_mfma_f32_16x16x32_bf16 v[82:85], v[174:177], v[222:225], v[82:85]
	v_mfma_f32_16x16x32_bf16 v[110:113], v[178:181], v[194:197], v[110:113]
	v_mfma_f32_16x16x32_bf16 v[106:109], v[186:189], v[194:197], v[106:109]
	v_mfma_f32_16x16x32_bf16 v[94:97], v[178:181], v[202:205], v[94:97]
	v_mfma_f32_16x16x32_bf16 v[90:93], v[186:189], v[202:205], v[90:93]
	v_mfma_f32_16x16x32_bf16 v[78:81], v[178:181], v[210:213], v[78:81]
	v_mfma_f32_16x16x32_bf16 v[74:77], v[186:189], v[210:213], v[74:77]
	v_mfma_f32_16x16x32_bf16 v[70:73], v[178:181], v[218:221], v[70:73]
	v_mfma_f32_16x16x32_bf16 v[66:69], v[186:189], v[218:221], v[66:69]
	v_mfma_f32_16x16x32_bf16 v[110:113], v[182:185], v[198:201], v[110:113]
	v_mfma_f32_16x16x32_bf16 v[106:109], v[190:193], v[198:201], v[106:109]
	v_mfma_f32_16x16x32_bf16 v[94:97], v[182:185], v[206:209], v[94:97]
	v_mfma_f32_16x16x32_bf16 v[90:93], v[190:193], v[206:209], v[90:93]
	v_mfma_f32_16x16x32_bf16 v[78:81], v[182:185], v[214:217], v[78:81]
	v_mfma_f32_16x16x32_bf16 v[74:77], v[190:193], v[214:217], v[74:77]
	v_mfma_f32_16x16x32_bf16 v[70:73], v[182:185], v[222:225], v[70:73]
	v_mfma_f32_16x16x32_bf16 v[66:69], v[190:193], v[222:225], v[66:69]
	s_barrier
	s_add_i32 s33, s82, s25
	v_lshl_add_u64 v[156:157], s[54:55], 0, v[134:135]
	s_mov_b32 m0, s33
	ds_read_b128 v[194:197], v165 offset:16384
	ds_read_b128 v[198:201], v165 offset:17408
	ds_read_b128 v[202:205], v165 offset:18432
	ds_read_b128 v[206:209], v165 offset:19456
	ds_read_b128 v[210:213], v165 offset:20480
	ds_read_b128 v[214:217], v165 offset:21504
	ds_read_b128 v[218:221], v165 offset:22528
	ds_read_b128 v[222:225], v165 offset:23552
	global_load_lds_dwordx4 v[156:157], off
	s_add_i32 m0, s33, 0x2000
	s_add_u32 s94, s54, 0x40000
	v_lshl_add_u64 v[226:227], s[54:55], 0, v[130:131]
	s_addc_u32 s95, s55, 0
	s_add_i32 s33, s83, s25
	global_load_lds_dwordx4 v[226:227], off
	v_lshl_add_u64 v[230:231], s[94:95], 0, v[134:135]
	s_mov_b32 m0, s33
	v_lshl_add_u64 v[232:233], s[56:57], 0, v[132:133]
	global_load_lds_dwordx4 v[230:231], off
	v_lshl_add_u64 v[230:231], s[94:95], 0, v[130:131]
	s_add_i32 m0, s33, 0x2000
	s_nop 0
	global_load_lds_dwordx4 v[230:231], off
	v_lshl_add_u64 v[230:231], s[56:57], 0, v[136:137]
	s_mov_b32 m0, s26
	s_nop 0
	global_load_lds_dwordx4 v[230:231], off
	s_mov_b32 m0, s27
	s_nop 0
	global_load_lds_dwordx4 v[232:233], off
	s_waitcnt vmcnt(8)
	s_waitcnt lgkmcnt(0)
	s_barrier
	s_waitcnt lgkmcnt(0)
	v_mfma_f32_16x16x32_bf16 v[62:65], v[152:155], v[194:197], v[62:65]
	v_mfma_f32_16x16x32_bf16 v[58:61], v[170:173], v[194:197], v[58:61]
	v_mfma_f32_16x16x32_bf16 v[54:57], v[152:155], v[202:205], v[54:57]
	v_mfma_f32_16x16x32_bf16 v[50:53], v[170:173], v[202:205], v[50:53]
	v_mfma_f32_16x16x32_bf16 v[38:41], v[152:155], v[210:213], v[38:41]
	v_mfma_f32_16x16x32_bf16 v[34:37], v[170:173], v[210:213], v[34:37]
	v_mfma_f32_16x16x32_bf16 v[22:25], v[152:155], v[218:221], v[22:25]
	v_mfma_f32_16x16x32_bf16 v[18:21], v[170:173], v[218:221], v[18:21]
	v_mfma_f32_16x16x32_bf16 v[62:65], v[166:169], v[198:201], v[62:65]
	v_mfma_f32_16x16x32_bf16 v[58:61], v[174:177], v[198:201], v[58:61]
	v_mfma_f32_16x16x32_bf16 v[54:57], v[166:169], v[206:209], v[54:57]
	v_mfma_f32_16x16x32_bf16 v[50:53], v[174:177], v[206:209], v[50:53]
	v_mfma_f32_16x16x32_bf16 v[38:41], v[166:169], v[214:217], v[38:41]
	v_mfma_f32_16x16x32_bf16 v[34:37], v[174:177], v[214:217], v[34:37]
	v_mfma_f32_16x16x32_bf16 v[22:25], v[166:169], v[222:225], v[22:25]
	v_mfma_f32_16x16x32_bf16 v[18:21], v[174:177], v[222:225], v[18:21]
	v_mfma_f32_16x16x32_bf16 v[46:49], v[178:181], v[194:197], v[46:49]
	v_mfma_f32_16x16x32_bf16 v[42:45], v[186:189], v[194:197], v[42:45]
	v_mfma_f32_16x16x32_bf16 v[30:33], v[178:181], v[202:205], v[30:33]
	v_mfma_f32_16x16x32_bf16 v[26:29], v[186:189], v[202:205], v[26:29]
	v_mfma_f32_16x16x32_bf16 v[14:17], v[178:181], v[210:213], v[14:17]
	v_mfma_f32_16x16x32_bf16 v[10:13], v[186:189], v[210:213], v[10:13]
	v_mfma_f32_16x16x32_bf16 v[6:9], v[178:181], v[218:221], v[6:9]
	v_mfma_f32_16x16x32_bf16 v[2:5], v[186:189], v[218:221], v[2:5]
	v_mfma_f32_16x16x32_bf16 v[46:49], v[182:185], v[198:201], v[46:49]
	v_mfma_f32_16x16x32_bf16 v[42:45], v[190:193], v[198:201], v[42:45]
	v_mfma_f32_16x16x32_bf16 v[30:33], v[182:185], v[206:209], v[30:33]
	v_mfma_f32_16x16x32_bf16 v[26:29], v[190:193], v[206:209], v[26:29]
	v_mfma_f32_16x16x32_bf16 v[14:17], v[182:185], v[214:217], v[14:17]
	v_mfma_f32_16x16x32_bf16 v[10:13], v[190:193], v[214:217], v[10:13]
	v_mfma_f32_16x16x32_bf16 v[6:9], v[182:185], v[222:225], v[6:9]
	v_mfma_f32_16x16x32_bf16 v[2:5], v[190:193], v[222:225], v[2:5]
	s_barrier
	s_add_i32 s33, 0, 0x18000
	v_add_u32_e32 v138, s33, v158
	s_add_i32 s80, 0, 0x1c000
	ds_read_b128 v[152:155], v138
	ds_read_b128 v[166:169], v138 offset:1024
	ds_read_b128 v[170:173], v138 offset:2048
	ds_read_b128 v[174:177], v138 offset:3072
	v_add_u32_e32 v138, s80, v158
	ds_read_b128 v[178:181], v138
	ds_read_b128 v[182:185], v138 offset:1024
	ds_read_b128 v[186:189], v138 offset:2048
	ds_read_b128 v[190:193], v138 offset:3072
	s_add_u32 s56, s56, 0x40000
	s_addc_u32 s57, s57, 0
	s_mov_b32 m0, s58
	v_lshl_add_u64 v[234:235], s[56:57], 0, v[136:137]
	ds_read_b128 v[194:197], v165 offset:32768
	ds_read_b128 v[198:201], v165 offset:33792
	ds_read_b128 v[202:205], v165 offset:34816
	ds_read_b128 v[206:209], v165 offset:35840
	ds_read_b128 v[210:213], v165 offset:36864
	ds_read_b128 v[214:217], v165 offset:37888
	ds_read_b128 v[218:221], v165 offset:38912
	ds_read_b128 v[222:225], v165 offset:39936
	global_load_lds_dwordx4 v[234:235], off
	v_lshl_add_u64 v[234:235], s[56:57], 0, v[132:133]
	s_mov_b32 m0, s59
	s_nop 0
	global_load_lds_dwordx4 v[234:235], off
	s_waitcnt vmcnt(8)
	s_waitcnt lgkmcnt(0)
	s_barrier
	s_waitcnt lgkmcnt(0)
	v_mfma_f32_16x16x32_bf16 v[126:129], v[152:155], v[194:197], v[126:129]
	v_mfma_f32_16x16x32_bf16 v[122:125], v[170:173], v[194:197], v[122:125]
	v_mfma_f32_16x16x32_bf16 v[118:121], v[152:155], v[202:205], v[118:121]
	v_mfma_f32_16x16x32_bf16 v[114:117], v[170:173], v[202:205], v[114:117]
	v_mfma_f32_16x16x32_bf16 v[102:105], v[152:155], v[210:213], v[102:105]
	v_mfma_f32_16x16x32_bf16 v[98:101], v[170:173], v[210:213], v[98:101]
	v_mfma_f32_16x16x32_bf16 v[86:89], v[152:155], v[218:221], v[86:89]
	v_mfma_f32_16x16x32_bf16 v[82:85], v[170:173], v[218:221], v[82:85]
	v_mfma_f32_16x16x32_bf16 v[126:129], v[166:169], v[198:201], v[126:129]
	v_mfma_f32_16x16x32_bf16 v[122:125], v[174:177], v[198:201], v[122:125]
	v_mfma_f32_16x16x32_bf16 v[118:121], v[166:169], v[206:209], v[118:121]
	v_mfma_f32_16x16x32_bf16 v[114:117], v[174:177], v[206:209], v[114:117]
	v_mfma_f32_16x16x32_bf16 v[102:105], v[166:169], v[214:217], v[102:105]
	v_mfma_f32_16x16x32_bf16 v[98:101], v[174:177], v[214:217], v[98:101]
	v_mfma_f32_16x16x32_bf16 v[86:89], v[166:169], v[222:225], v[86:89]
	v_mfma_f32_16x16x32_bf16 v[82:85], v[174:177], v[222:225], v[82:85]
	v_mfma_f32_16x16x32_bf16 v[110:113], v[178:181], v[194:197], v[110:113]
	v_mfma_f32_16x16x32_bf16 v[106:109], v[186:189], v[194:197], v[106:109]
	v_mfma_f32_16x16x32_bf16 v[94:97], v[178:181], v[202:205], v[94:97]
	v_mfma_f32_16x16x32_bf16 v[90:93], v[186:189], v[202:205], v[90:93]
	v_mfma_f32_16x16x32_bf16 v[78:81], v[178:181], v[210:213], v[78:81]
	v_mfma_f32_16x16x32_bf16 v[74:77], v[186:189], v[210:213], v[74:77]
	v_mfma_f32_16x16x32_bf16 v[70:73], v[178:181], v[218:221], v[70:73]
	v_mfma_f32_16x16x32_bf16 v[66:69], v[186:189], v[218:221], v[66:69]
	v_mfma_f32_16x16x32_bf16 v[110:113], v[182:185], v[198:201], v[110:113]
	v_mfma_f32_16x16x32_bf16 v[106:109], v[190:193], v[198:201], v[106:109]
	v_mfma_f32_16x16x32_bf16 v[94:97], v[182:185], v[206:209], v[94:97]
	v_mfma_f32_16x16x32_bf16 v[90:93], v[190:193], v[206:209], v[90:93]
	v_mfma_f32_16x16x32_bf16 v[78:81], v[182:185], v[214:217], v[78:81]
	v_mfma_f32_16x16x32_bf16 v[74:77], v[190:193], v[214:217], v[74:77]
	v_mfma_f32_16x16x32_bf16 v[70:73], v[182:185], v[222:225], v[70:73]
	v_mfma_f32_16x16x32_bf16 v[66:69], v[190:193], v[222:225], v[66:69]
	s_barrier
	s_add_i32 s33, s33, s25
	v_lshl_add_u64 v[156:157], v[156:157], 0, s[12:13]
	s_mov_b32 m0, s33
	ds_read_b128 v[194:197], v165 offset:49152
	ds_read_b128 v[198:201], v165 offset:50176
	ds_read_b128 v[202:205], v165 offset:51200
	ds_read_b128 v[206:209], v165 offset:52224
	ds_read_b128 v[210:213], v165 offset:53248
	ds_read_b128 v[214:217], v165 offset:54272
	ds_read_b128 v[218:221], v165 offset:55296
	ds_read_b128 v[222:225], v165 offset:56320
	global_load_lds_dwordx4 v[156:157], off
	s_add_i32 m0, s33, 0x2000
	s_add_u32 s54, s54, 0x40080
	v_lshl_add_u64 v[156:157], v[226:227], 0, s[12:13]
	s_addc_u32 s55, s55, 0
	s_add_i32 s33, s80, s25
	global_load_lds_dwordx4 v[156:157], off
	v_lshl_add_u64 v[156:157], s[54:55], 0, v[134:135]
	s_mov_b32 m0, s33
	s_nop 0
	global_load_lds_dwordx4 v[156:157], off
	v_lshl_add_u64 v[156:157], s[54:55], 0, v[130:131]
	s_add_i32 m0, s33, 0x2000
	s_nop 0
	global_load_lds_dwordx4 v[156:157], off
	v_lshl_add_u64 v[156:157], v[230:231], 0, s[12:13]
	s_mov_b32 m0, s62
	s_nop 0
	global_load_lds_dwordx4 v[156:157], off
	v_lshl_add_u64 v[156:157], v[232:233], 0, s[12:13]
	s_mov_b32 m0, s63
	s_nop 0
	global_load_lds_dwordx4 v[156:157], off
	s_waitcnt vmcnt(8)
	s_waitcnt lgkmcnt(0)
	s_barrier
	s_waitcnt lgkmcnt(0)
	v_mfma_f32_16x16x32_bf16 v[62:65], v[152:155], v[194:197], v[62:65]
	v_mfma_f32_16x16x32_bf16 v[58:61], v[170:173], v[194:197], v[58:61]
	v_mfma_f32_16x16x32_bf16 v[54:57], v[152:155], v[202:205], v[54:57]
	v_mfma_f32_16x16x32_bf16 v[50:53], v[170:173], v[202:205], v[50:53]
	v_mfma_f32_16x16x32_bf16 v[38:41], v[152:155], v[210:213], v[38:41]
	v_mfma_f32_16x16x32_bf16 v[34:37], v[170:173], v[210:213], v[34:37]
	v_mfma_f32_16x16x32_bf16 v[22:25], v[152:155], v[218:221], v[22:25]
	v_mfma_f32_16x16x32_bf16 v[18:21], v[170:173], v[218:221], v[18:21]
	v_mfma_f32_16x16x32_bf16 v[62:65], v[166:169], v[198:201], v[62:65]
	v_mfma_f32_16x16x32_bf16 v[58:61], v[174:177], v[198:201], v[58:61]
	v_mfma_f32_16x16x32_bf16 v[54:57], v[166:169], v[206:209], v[54:57]
	v_mfma_f32_16x16x32_bf16 v[50:53], v[174:177], v[206:209], v[50:53]
	v_mfma_f32_16x16x32_bf16 v[38:41], v[166:169], v[214:217], v[38:41]
	v_mfma_f32_16x16x32_bf16 v[34:37], v[174:177], v[214:217], v[34:37]
	v_mfma_f32_16x16x32_bf16 v[22:25], v[166:169], v[222:225], v[22:25]
	v_mfma_f32_16x16x32_bf16 v[18:21], v[174:177], v[222:225], v[18:21]
	v_mfma_f32_16x16x32_bf16 v[46:49], v[178:181], v[194:197], v[46:49]
	v_mfma_f32_16x16x32_bf16 v[42:45], v[186:189], v[194:197], v[42:45]
	v_mfma_f32_16x16x32_bf16 v[30:33], v[178:181], v[202:205], v[30:33]
	v_mfma_f32_16x16x32_bf16 v[26:29], v[186:189], v[202:205], v[26:29]
	v_mfma_f32_16x16x32_bf16 v[14:17], v[178:181], v[210:213], v[14:17]
	v_mfma_f32_16x16x32_bf16 v[10:13], v[186:189], v[210:213], v[10:13]
	v_mfma_f32_16x16x32_bf16 v[6:9], v[178:181], v[218:221], v[6:9]
	v_mfma_f32_16x16x32_bf16 v[2:5], v[186:189], v[218:221], v[2:5]
	v_mfma_f32_16x16x32_bf16 v[46:49], v[182:185], v[198:201], v[46:49]
	v_mfma_f32_16x16x32_bf16 v[42:45], v[190:193], v[198:201], v[42:45]
	v_mfma_f32_16x16x32_bf16 v[30:33], v[182:185], v[206:209], v[30:33]
	v_mfma_f32_16x16x32_bf16 v[26:29], v[190:193], v[206:209], v[26:29]
	v_mfma_f32_16x16x32_bf16 v[14:17], v[182:185], v[214:217], v[14:17]
	v_mfma_f32_16x16x32_bf16 v[10:13], v[190:193], v[214:217], v[10:13]
	v_mfma_f32_16x16x32_bf16 v[6:9], v[182:185], v[222:225], v[6:9]
	v_mfma_f32_16x16x32_bf16 v[2:5], v[190:193], v[222:225], v[2:5]
	s_barrier
	s_add_i32 s92, s92, 2
	s_add_u32 s52, s52, 0x100
	s_addc_u32 s53, s53, 0
	s_add_u32 s90, s90, 0x100
	s_addc_u32 s91, s91, 0
	s_cmp_gt_u32 s92, 13
	s_cbranch_scc0 .LBB0_163
	s_and_b64 vcc, exec, s[14:15]
	s_cbranch_vccz .LBB0_166
	s_barrier

.LBB0_185:
	s_setprio 0
	s_waitcnt vmcnt(0)
	v_readlane_b32 s26, v254, 38
	v_readlane_b32 s27, v254, 39
	s_barrier
